# attention tile bodies hand-written for the unbiased path (DK=64, DK=96): K/V fragment LDS reads issued ahead of MFMAs with counted lgkmcnt, no vmcnt(0) drain in MLA loop, tree sums
# speedup vs baseline: 1.0465x; 1.0246x over previous
.LBB0_383:
	s_and_b32 s2, s27, 3
	v_lshl_or_b32 v107, s2, 14, v103
	v_add_u32_e32 v36, v107, v115
	v_add_u32_e32 v37, v107, v116
	v_add_u32_e32 v38, v107, v117
	v_add_u32_e32 v39, v107, v118
	v_add_u32_e32 v40, v107, v119
	v_add_u32_e32 v41, v107, v120
	ds_read_b128 v[132:135], v36
	ds_read_b128 v[136:139], v37
	ds_read_b128 v[140:143], v38
	ds_read_b128 v[144:147], v39
	ds_read_b128 v[148:151], v40
	ds_read_b128 v[152:155], v41
	ds_read_b128 v[156:159], v36 offset:8192
	ds_read_b128 v[160:163], v37 offset:8192
	ds_read_b128 v[164:167], v38 offset:8192
	ds_read_b128 v[168:171], v39 offset:8192
	ds_read_b128 v[172:175], v40 offset:8192
	ds_read_b128 v[176:179], v41 offset:8192
	v_lshl_add_u32 v114, s2, 13, v129
	s_waitcnt lgkmcnt(11)
	v_mfma_f32_32x32x16_bf16 v[52:67], v[132:135], v[68:71], 0
	s_waitcnt lgkmcnt(10)
	v_mfma_f32_32x32x16_bf16 v[52:67], v[136:139], v[72:75], v[52:67]
	s_waitcnt lgkmcnt(9)
	v_mfma_f32_32x32x16_bf16 v[52:67], v[140:143], v[76:79], v[52:67]
	s_waitcnt lgkmcnt(8)
	v_mfma_f32_32x32x16_bf16 v[52:67], v[144:147], v[80:83], v[52:67]
	s_waitcnt lgkmcnt(7)
	v_mfma_f32_32x32x16_bf16 v[52:67], v[148:151], v[84:87], v[52:67]
	s_waitcnt lgkmcnt(6)
	v_mfma_f32_32x32x16_bf16 v[52:67], v[152:155], v[88:91], v[52:67]
	s_waitcnt lgkmcnt(5)
	v_mfma_f32_32x32x16_bf16 v[36:51], v[156:159], v[68:71], 0
	s_waitcnt lgkmcnt(4)
	v_mfma_f32_32x32x16_bf16 v[36:51], v[160:163], v[72:75], v[36:51]
	s_waitcnt lgkmcnt(3)
	v_mfma_f32_32x32x16_bf16 v[36:51], v[164:167], v[76:79], v[36:51]
	s_waitcnt lgkmcnt(2)
	v_mfma_f32_32x32x16_bf16 v[36:51], v[168:171], v[80:83], v[36:51]
	s_waitcnt lgkmcnt(1)
	v_mfma_f32_32x32x16_bf16 v[36:51], v[172:175], v[84:87], v[36:51]
	s_waitcnt lgkmcnt(0)
	v_mfma_f32_32x32x16_bf16 v[36:51], v[176:179], v[88:91], v[36:51]
	v_add_u32_e32 v164, v114, v121
	v_add_u32_e32 v165, v114, v122
	v_add_u32_e32 v166, v114, v123
	v_add_u32_e32 v167, v114, v124
	v_add_u32_e32 v168, v114, v125
	v_add_u32_e32 v169, v114, v126
	v_add_u32_e32 v170, v114, v127
	v_add_u32_e32 v171, v114, v128
	ds_read_b64 v[132:133], v164
	ds_read_b64 v[134:135], v165
	ds_read_b64 v[136:137], v166
	ds_read_b64 v[138:139], v167
	ds_read_b64 v[140:141], v168
	ds_read_b64 v[142:143], v169
	ds_read_b64 v[144:145], v170
	ds_read_b64 v[146:147], v171
	ds_read_b64 v[148:149], v164 offset:4096
	ds_read_b64 v[150:151], v165 offset:4096
	ds_read_b64 v[152:153], v166 offset:4096
	ds_read_b64 v[154:155], v167 offset:4096
	ds_read_b64 v[156:157], v168 offset:4096
	ds_read_b64 v[158:159], v169 offset:4096
	ds_read_b64 v[160:161], v170 offset:4096
	ds_read_b64 v[162:163], v171 offset:4096
	v_max3_f32 v107, v52, v53, v54
	v_max3_f32 v114, v36, v37, v38
	v_max3_f32 v107, v107, v55, v56
	v_max3_f32 v114, v114, v39, v40
	v_max3_f32 v107, v107, v57, v58
	v_max3_f32 v114, v114, v41, v42
	v_max3_f32 v107, v107, v59, v60
	v_max3_f32 v114, v114, v43, v44
	v_max3_f32 v107, v107, v61, v62
	v_max3_f32 v114, v114, v45, v46
	v_max3_f32 v107, v107, v63, v64
	v_max3_f32 v114, v114, v47, v48
	v_max3_f32 v107, v107, v65, v66
	v_max3_f32 v114, v114, v49, v50
	v_max3_f32 v107, v107, v67, v51
	v_max_f32_e32 v107, v107, v114
	v_mul_f32_e32 v107, s33, v107
	v_mov_b32_e32 v172, v107
	s_nop 1
	v_permlane32_swap_b32 v107, v172
	s_nop 1
	v_max3_f32 v107, v131, v107, v172
	v_sub_f32_e32 v114, v131, v107
	v_exp_f32_e32 v114, v114
	v_cmp_neq_f32_e32 vcc, v107, v131
	s_cbranch_vccz .Lat96_keep
	v_pk_mul_f32 v[34:35], v[34:35], v[114:115] op_sel_hi:[1,0]
	v_pk_mul_f32 v[32:33], v[32:33], v[114:115] op_sel_hi:[1,0]
	v_pk_mul_f32 v[30:31], v[30:31], v[114:115] op_sel_hi:[1,0]
	v_pk_mul_f32 v[28:29], v[28:29], v[114:115] op_sel_hi:[1,0]
	v_pk_mul_f32 v[26:27], v[26:27], v[114:115] op_sel_hi:[1,0]
	v_pk_mul_f32 v[24:25], v[24:25], v[114:115] op_sel_hi:[1,0]
	v_pk_mul_f32 v[22:23], v[22:23], v[114:115] op_sel_hi:[1,0]
	v_pk_mul_f32 v[20:21], v[20:21], v[114:115] op_sel_hi:[1,0]
	v_pk_mul_f32 v[18:19], v[18:19], v[114:115] op_sel_hi:[1,0]
	v_pk_mul_f32 v[16:17], v[16:17], v[114:115] op_sel_hi:[1,0]
	v_pk_mul_f32 v[14:15], v[14:15], v[114:115] op_sel_hi:[1,0]
	v_pk_mul_f32 v[12:13], v[12:13], v[114:115] op_sel_hi:[1,0]
	v_pk_mul_f32 v[10:11], v[10:11], v[114:115] op_sel_hi:[1,0]
	v_pk_mul_f32 v[8:9], v[8:9], v[114:115] op_sel_hi:[1,0]
	v_pk_mul_f32 v[6:7], v[6:7], v[114:115] op_sel_hi:[1,0]
	v_pk_mul_f32 v[4:5], v[4:5], v[114:115] op_sel_hi:[1,0]
.Lat96_keep:
	v_fma_f32 v52, v52, s33, -v107
	v_fma_f32 v53, v53, s33, -v107
	v_fma_f32 v54, v54, s33, -v107
	v_fma_f32 v55, v55, s33, -v107
	v_fma_f32 v56, v56, s33, -v107
	v_fma_f32 v57, v57, s33, -v107
	v_fma_f32 v58, v58, s33, -v107
	v_fma_f32 v59, v59, s33, -v107
	v_exp_f32_e32 v52, v52
	v_exp_f32_e32 v53, v53
	v_exp_f32_e32 v54, v54
	v_exp_f32_e32 v55, v55
	v_exp_f32_e32 v56, v56
	v_exp_f32_e32 v57, v57
	v_exp_f32_e32 v58, v58
	v_exp_f32_e32 v59, v59
	v_cvt_pk_bf16_f32 v164, v52, v53
	v_cvt_pk_bf16_f32 v165, v54, v55
	v_cvt_pk_bf16_f32 v166, v56, v57
	v_cvt_pk_bf16_f32 v167, v58, v59
	v_add_f32_e32 v52, v52, v53
	v_add_f32_e32 v54, v54, v55
	v_add_f32_e32 v56, v56, v57
	v_add_f32_e32 v58, v58, v59
	v_add_f32_e32 v52, v52, v54
	v_add_f32_e32 v56, v56, v58
	v_add_f32_e32 v52, v52, v56
	v_fma_f32 v60, v60, s33, -v107
	v_fma_f32 v61, v61, s33, -v107
	v_fma_f32 v62, v62, s33, -v107
	v_fma_f32 v63, v63, s33, -v107
	v_fma_f32 v64, v64, s33, -v107
	v_fma_f32 v65, v65, s33, -v107
	v_fma_f32 v66, v66, s33, -v107
	v_fma_f32 v67, v67, s33, -v107
	v_exp_f32_e32 v60, v60
	v_exp_f32_e32 v61, v61
	v_exp_f32_e32 v62, v62
	v_exp_f32_e32 v63, v63
	v_exp_f32_e32 v64, v64
	v_exp_f32_e32 v65, v65
	v_exp_f32_e32 v66, v66
	v_exp_f32_e32 v67, v67
	v_cvt_pk_bf16_f32 v168, v60, v61
	v_cvt_pk_bf16_f32 v169, v62, v63
	v_cvt_pk_bf16_f32 v170, v64, v65
	v_cvt_pk_bf16_f32 v171, v66, v67
	v_add_f32_e32 v60, v60, v61
	v_add_f32_e32 v62, v62, v63
	v_add_f32_e32 v64, v64, v65
	v_add_f32_e32 v66, v66, v67
	v_add_f32_e32 v60, v60, v62
	v_add_f32_e32 v64, v64, v66
	v_add_f32_e32 v60, v60, v64
	v_fma_f32 v36, v36, s33, -v107
	v_fma_f32 v37, v37, s33, -v107
	v_fma_f32 v38, v38, s33, -v107
	v_fma_f32 v39, v39, s33, -v107
	v_fma_f32 v40, v40, s33, -v107
	v_fma_f32 v41, v41, s33, -v107
	v_fma_f32 v42, v42, s33, -v107
	v_fma_f32 v43, v43, s33, -v107
	v_exp_f32_e32 v36, v36
	v_exp_f32_e32 v37, v37
	v_exp_f32_e32 v38, v38
	v_exp_f32_e32 v39, v39
	v_exp_f32_e32 v40, v40
	v_exp_f32_e32 v41, v41
	v_exp_f32_e32 v42, v42
	v_exp_f32_e32 v43, v43
	v_cvt_pk_bf16_f32 v172, v36, v37
	v_cvt_pk_bf16_f32 v173, v38, v39
	v_cvt_pk_bf16_f32 v174, v40, v41
	v_cvt_pk_bf16_f32 v175, v42, v43
	v_add_f32_e32 v36, v36, v37
	v_add_f32_e32 v38, v38, v39
	v_add_f32_e32 v40, v40, v41
	v_add_f32_e32 v42, v42, v43
	v_add_f32_e32 v36, v36, v38
	v_add_f32_e32 v40, v40, v42
	v_add_f32_e32 v36, v36, v40
	v_fma_f32 v44, v44, s33, -v107
	v_fma_f32 v45, v45, s33, -v107
	v_fma_f32 v46, v46, s33, -v107
	v_fma_f32 v47, v47, s33, -v107
	v_fma_f32 v48, v48, s33, -v107
	v_fma_f32 v49, v49, s33, -v107
	v_fma_f32 v50, v50, s33, -v107
	v_fma_f32 v51, v51, s33, -v107
	v_exp_f32_e32 v44, v44
	v_exp_f32_e32 v45, v45
	v_exp_f32_e32 v46, v46
	v_exp_f32_e32 v47, v47
	v_exp_f32_e32 v48, v48
	v_exp_f32_e32 v49, v49
	v_exp_f32_e32 v50, v50
	v_exp_f32_e32 v51, v51
	v_cvt_pk_bf16_f32 v176, v44, v45
	v_cvt_pk_bf16_f32 v177, v46, v47
	v_cvt_pk_bf16_f32 v178, v48, v49
	v_cvt_pk_bf16_f32 v179, v50, v51
	v_add_f32_e32 v44, v44, v45
	v_add_f32_e32 v46, v46, v47
	v_add_f32_e32 v48, v48, v49
	v_add_f32_e32 v50, v50, v51
	v_add_f32_e32 v44, v44, v46
	v_add_f32_e32 v48, v48, v50
	v_add_f32_e32 v44, v44, v48
	v_add_f32_e32 v52, v52, v60
	v_add_f32_e32 v36, v36, v44
	v_add_f32_e32 v52, v52, v36
	v_fma_f32 v36, v130, v114, v52
	s_waitcnt lgkmcnt(0)
	v_mfma_f32_32x32x16_bf16 v[20:35], v[132:135], v[164:167], v[20:35]
	v_mfma_f32_32x32x16_bf16 v[20:35], v[136:139], v[168:171], v[20:35]
	v_mfma_f32_32x32x16_bf16 v[20:35], v[140:143], v[172:175], v[20:35]
	v_mfma_f32_32x32x16_bf16 v[20:35], v[144:147], v[176:179], v[20:35]
	v_mfma_f32_32x32x16_bf16 v[4:19], v[148:151], v[164:167], v[4:19]
	v_mfma_f32_32x32x16_bf16 v[4:19], v[152:155], v[168:171], v[4:19]
	v_mfma_f32_32x32x16_bf16 v[4:19], v[156:159], v[172:175], v[4:19]
	v_mfma_f32_32x32x16_bf16 v[4:19], v[160:163], v[176:179], v[4:19]
	s_add_i32 s27, s27, 1
	s_add_i32 s26, s26, -1
	s_cmp_lg_u32 s26, -1
	s_cbranch_scc1 .LBB0_373

.LBB0_417:
	s_and_saveexec_b64 s[36:37], s[96:97]
	s_cbranch_execz .LBB0_404
	s_andn2_b64 vcc, exec, s[94:95]
	s_cbranch_vccz .Lat64_fast
	s_and_b32 s2, s49, 3
	v_lshl_or_b32 v2, s2, 14, v101
	v_add_u32_e32 v40, v2, v102
	ds_read_b128 v[36:39], v40
	s_setprio 1
	s_waitcnt lgkmcnt(0)
	v_mfma_f32_32x32x16_bf16 v[52:67], v[36:39], v[68:71], 0
	s_setprio 0
	v_add_u32_e32 v117, v2, v103
	ds_read_b128 v[36:39], v117
	s_setprio 1
	s_waitcnt lgkmcnt(0)
	v_mfma_f32_32x32x16_bf16 v[52:67], v[36:39], v[72:75], v[52:67]
	s_setprio 0
	v_add_u32_e32 v122, v2, v104
	ds_read_b128 v[36:39], v122
	s_setprio 1
	s_waitcnt lgkmcnt(0)
	v_mfma_f32_32x32x16_bf16 v[52:67], v[36:39], v[76:79], v[52:67]
	s_setprio 0
	v_add_u32_e32 v2, v2, v105
	ds_read_b128 v[36:39], v2
	s_setprio 1
	s_waitcnt lgkmcnt(0)
	v_mfma_f32_32x32x16_bf16 v[52:67], v[36:39], v[80:83], v[52:67]
	s_setprio 0
	ds_read_b128 v[36:39], v40 offset:4096
	s_setprio 1
	s_waitcnt lgkmcnt(0)
	v_mfma_f32_32x32x16_bf16 v[36:51], v[36:39], v[68:71], 0
	s_setprio 0
	ds_read_b128 v[118:121], v117 offset:4096
	s_setprio 1
	s_waitcnt lgkmcnt(0)
	v_mfma_f32_32x32x16_bf16 v[36:51], v[118:121], v[72:75], v[36:51]
	s_setprio 0
	ds_read_b128 v[118:121], v122 offset:4096
	s_setprio 1
	s_waitcnt lgkmcnt(0)
	v_mfma_f32_32x32x16_bf16 v[36:51], v[118:121], v[76:79], v[36:51]
	s_setprio 0
	ds_read_b128 v[118:121], v2 offset:4096
	s_setprio 1
	s_waitcnt lgkmcnt(0)
	v_mfma_f32_32x32x16_bf16 v[36:51], v[118:121], v[80:83], v[36:51]
	s_setprio 0
	s_andn2_b64 vcc, exec, s[94:95]
	s_mov_b64 s[96:97], -1
	s_cbranch_vccnz .LBB0_420
	s_mov_b32 s3, 0xf149f2ca
	v_max3_f32 v2, v52, s3, v53
	v_max3_f32 v2, v2, v54, v55
	v_max3_f32 v2, v2, v56, v57
	v_max3_f32 v2, v2, v58, v59
	v_max3_f32 v2, v2, v60, v61
	v_max3_f32 v2, v2, v62, v63
	v_max3_f32 v2, v2, v64, v65
	v_max3_f32 v2, v2, v66, v67
	v_max3_f32 v2, v2, v36, v37
	v_max3_f32 v2, v2, v38, v39
	v_max3_f32 v2, v2, v40, v41
	v_max3_f32 v2, v2, v42, v43
	v_max3_f32 v2, v2, v44, v45
	v_max3_f32 v2, v2, v46, v47
	v_max3_f32 v2, v2, v48, v49
	v_max3_f32 v2, v2, v50, v51
	v_mul_f32_e32 v2, 0x3e38aa3b, v2
	s_mov_b64 s[96:97], 0
	v_mov_b32_e32 v118, v52
	v_mov_b32_e32 v117, v53
	v_mov_b32_e32 v120, v54
	v_mov_b32_e32 v119, v55
	v_mov_b32_e32 v122, v56
	v_mov_b32_e32 v121, v57
	v_mov_b32_e32 v124, v58
	v_mov_b32_e32 v123, v59
	v_mov_b32_e32 v126, v60
	v_mov_b32_e32 v125, v61
	v_mov_b32_e32 v128, v62
	v_mov_b32_e32 v127, v63
	v_mov_b32_e32 v130, v64
	v_mov_b32_e32 v129, v65
	v_mov_b32_e32 v132, v66
	v_mov_b32_e32 v131, v67
	v_mov_b32_e32 v134, v36
	v_mov_b32_e32 v133, v37
	v_mov_b32_e32 v136, v38
	v_mov_b32_e32 v135, v39
	v_mov_b32_e32 v138, v40
	v_mov_b32_e32 v137, v41
	v_mov_b32_e32 v140, v42
	v_mov_b32_e32 v139, v43
	v_mov_b32_e32 v142, v44
	v_mov_b32_e32 v141, v45
	v_mov_b32_e32 v144, v46
	v_mov_b32_e32 v143, v47
	v_mov_b32_e32 v146, v48
	v_mov_b32_e32 v145, v49
	v_mov_b32_e32 v148, v50
	v_mov_b32_e32 v147, v51

.Lat64_fast:
	s_and_b32 s2, s49, 3
	v_lshl_or_b32 v2, s2, 14, v101
	v_add_u32_e32 v36, v2, v102
	v_add_u32_e32 v37, v2, v103
	v_add_u32_e32 v38, v2, v104
	v_add_u32_e32 v39, v2, v105
	ds_read_b128 v[118:121], v36
	ds_read_b128 v[122:125], v37
	ds_read_b128 v[126:129], v38
	ds_read_b128 v[130:133], v39
	ds_read_b128 v[134:137], v36 offset:4096
	ds_read_b128 v[138:141], v37 offset:4096
	ds_read_b128 v[142:145], v38 offset:4096
	ds_read_b128 v[146:149], v39 offset:4096
	v_lshl_add_u32 v170, s2, 13, v114
	s_waitcnt lgkmcnt(7)
	v_mfma_f32_32x32x16_bf16 v[52:67], v[118:121], v[68:71], 0
	s_waitcnt lgkmcnt(6)
	v_mfma_f32_32x32x16_bf16 v[52:67], v[122:125], v[72:75], v[52:67]
	s_waitcnt lgkmcnt(5)
	v_mfma_f32_32x32x16_bf16 v[52:67], v[126:129], v[76:79], v[52:67]
	s_waitcnt lgkmcnt(4)
	v_mfma_f32_32x32x16_bf16 v[52:67], v[130:133], v[80:83], v[52:67]
	s_waitcnt lgkmcnt(3)
	v_mfma_f32_32x32x16_bf16 v[36:51], v[134:137], v[68:71], 0
	s_waitcnt lgkmcnt(2)
	v_mfma_f32_32x32x16_bf16 v[36:51], v[138:141], v[72:75], v[36:51]
	s_waitcnt lgkmcnt(1)
	v_mfma_f32_32x32x16_bf16 v[36:51], v[142:145], v[76:79], v[36:51]
	s_waitcnt lgkmcnt(0)
	v_mfma_f32_32x32x16_bf16 v[36:51], v[146:149], v[80:83], v[36:51]
	v_add_u32_e32 v154, v170, v106
	v_add_u32_e32 v155, v170, v107
	v_add_u32_e32 v156, v170, v108
	v_add_u32_e32 v157, v170, v109
	v_add_u32_e32 v158, v170, v110
	v_add_u32_e32 v159, v170, v111
	v_add_u32_e32 v160, v170, v112
	v_add_u32_e32 v161, v170, v113
	ds_read_b64 v[118:119], v154
	ds_read_b64 v[120:121], v155
	ds_read_b64 v[122:123], v156
	ds_read_b64 v[124:125], v157
	ds_read_b64 v[126:127], v158
	ds_read_b64 v[128:129], v159
	ds_read_b64 v[130:131], v160
	ds_read_b64 v[132:133], v161
	ds_read_b64 v[134:135], v154 offset:4096
	ds_read_b64 v[136:137], v155 offset:4096
	ds_read_b64 v[138:139], v156 offset:4096
	ds_read_b64 v[140:141], v157 offset:4096
	ds_read_b64 v[142:143], v158 offset:4096
	ds_read_b64 v[144:145], v159 offset:4096
	ds_read_b64 v[146:147], v160 offset:4096
	ds_read_b64 v[148:149], v161 offset:4096
	v_max3_f32 v2, v52, v53, v54
	v_max3_f32 v170, v36, v37, v38
	v_max3_f32 v2, v2, v55, v56
	v_max3_f32 v170, v170, v39, v40
	v_max3_f32 v2, v2, v57, v58
	v_max3_f32 v170, v170, v41, v42
	v_max3_f32 v2, v2, v59, v60
	v_max3_f32 v170, v170, v43, v44
	v_max3_f32 v2, v2, v61, v62
	v_max3_f32 v170, v170, v45, v46
	v_max3_f32 v2, v2, v63, v64
	v_max3_f32 v170, v170, v47, v48
	v_max3_f32 v2, v2, v65, v66
	v_max3_f32 v170, v170, v49, v50
	v_max3_f32 v2, v2, v67, v51
	v_max_f32_e32 v2, v2, v170
	s_mov_b32 s3, 0x3e38aa3b
	v_mul_f32_e32 v2, s3, v2
	v_mov_b32_e32 v167, v2
	s_nop 1
	v_permlane32_swap_b32 v2, v167
	s_nop 1
	v_max3_f32 v166, v94, v2, v167
	v_sub_f32_e32 v168, v94, v166
	v_exp_f32_e32 v168, v168
	v_cmp_neq_f32_e32 vcc, v166, v94
	s_cbranch_vccz .Lat64_keep
	v_pk_mul_f32 v[34:35], v[34:35], v[168:169] op_sel_hi:[1,0]
	v_pk_mul_f32 v[32:33], v[32:33], v[168:169] op_sel_hi:[1,0]
	v_pk_mul_f32 v[30:31], v[30:31], v[168:169] op_sel_hi:[1,0]
	v_pk_mul_f32 v[28:29], v[28:29], v[168:169] op_sel_hi:[1,0]
	v_pk_mul_f32 v[26:27], v[26:27], v[168:169] op_sel_hi:[1,0]
	v_pk_mul_f32 v[24:25], v[24:25], v[168:169] op_sel_hi:[1,0]
	v_pk_mul_f32 v[22:23], v[22:23], v[168:169] op_sel_hi:[1,0]
	v_pk_mul_f32 v[20:21], v[20:21], v[168:169] op_sel_hi:[1,0]
	v_pk_mul_f32 v[18:19], v[18:19], v[168:169] op_sel_hi:[1,0]
	v_pk_mul_f32 v[16:17], v[16:17], v[168:169] op_sel_hi:[1,0]
	v_pk_mul_f32 v[14:15], v[14:15], v[168:169] op_sel_hi:[1,0]
	v_pk_mul_f32 v[12:13], v[12:13], v[168:169] op_sel_hi:[1,0]
	v_pk_mul_f32 v[10:11], v[10:11], v[168:169] op_sel_hi:[1,0]
	v_pk_mul_f32 v[8:9], v[8:9], v[168:169] op_sel_hi:[1,0]
	v_pk_mul_f32 v[6:7], v[6:7], v[168:169] op_sel_hi:[1,0]
	v_pk_mul_f32 v[4:5], v[4:5], v[168:169] op_sel_hi:[1,0]
.Lat64_keep:
	v_fma_f32 v52, v52, s3, -v166
	v_fma_f32 v53, v53, s3, -v166
	v_fma_f32 v54, v54, s3, -v166
	v_fma_f32 v55, v55, s3, -v166
	v_fma_f32 v56, v56, s3, -v166
	v_fma_f32 v57, v57, s3, -v166
	v_fma_f32 v58, v58, s3, -v166
	v_fma_f32 v59, v59, s3, -v166
	v_exp_f32_e32 v52, v52
	v_exp_f32_e32 v53, v53
	v_exp_f32_e32 v54, v54
	v_exp_f32_e32 v55, v55
	v_exp_f32_e32 v56, v56
	v_exp_f32_e32 v57, v57
	v_exp_f32_e32 v58, v58
	v_exp_f32_e32 v59, v59
	v_cvt_pk_bf16_f32 v150, v52, v53
	v_cvt_pk_bf16_f32 v151, v54, v55
	v_cvt_pk_bf16_f32 v152, v56, v57
	v_cvt_pk_bf16_f32 v153, v58, v59
	v_add_f32_e32 v52, v52, v53
	v_add_f32_e32 v54, v54, v55
	v_add_f32_e32 v56, v56, v57
	v_add_f32_e32 v58, v58, v59
	v_add_f32_e32 v52, v52, v54
	v_add_f32_e32 v56, v56, v58
	v_add_f32_e32 v52, v52, v56
	v_fma_f32 v60, v60, s3, -v166
	v_fma_f32 v61, v61, s3, -v166
	v_fma_f32 v62, v62, s3, -v166
	v_fma_f32 v63, v63, s3, -v166
	v_fma_f32 v64, v64, s3, -v166
	v_fma_f32 v65, v65, s3, -v166
	v_fma_f32 v66, v66, s3, -v166
	v_fma_f32 v67, v67, s3, -v166
	v_exp_f32_e32 v60, v60
	v_exp_f32_e32 v61, v61
	v_exp_f32_e32 v62, v62
	v_exp_f32_e32 v63, v63
	v_exp_f32_e32 v64, v64
	v_exp_f32_e32 v65, v65
	v_exp_f32_e32 v66, v66
	v_exp_f32_e32 v67, v67
	v_cvt_pk_bf16_f32 v154, v60, v61
	v_cvt_pk_bf16_f32 v155, v62, v63
	v_cvt_pk_bf16_f32 v156, v64, v65
	v_cvt_pk_bf16_f32 v157, v66, v67
	v_add_f32_e32 v60, v60, v61
	v_add_f32_e32 v62, v62, v63
	v_add_f32_e32 v64, v64, v65
	v_add_f32_e32 v66, v66, v67
	v_add_f32_e32 v60, v60, v62
	v_add_f32_e32 v64, v64, v66
	v_add_f32_e32 v60, v60, v64
	v_fma_f32 v36, v36, s3, -v166
	v_fma_f32 v37, v37, s3, -v166
	v_fma_f32 v38, v38, s3, -v166
	v_fma_f32 v39, v39, s3, -v166
	v_fma_f32 v40, v40, s3, -v166
	v_fma_f32 v41, v41, s3, -v166
	v_fma_f32 v42, v42, s3, -v166
	v_fma_f32 v43, v43, s3, -v166
	v_exp_f32_e32 v36, v36
	v_exp_f32_e32 v37, v37
	v_exp_f32_e32 v38, v38
	v_exp_f32_e32 v39, v39
	v_exp_f32_e32 v40, v40
	v_exp_f32_e32 v41, v41
	v_exp_f32_e32 v42, v42
	v_exp_f32_e32 v43, v43
	v_cvt_pk_bf16_f32 v158, v36, v37
	v_cvt_pk_bf16_f32 v159, v38, v39
	v_cvt_pk_bf16_f32 v160, v40, v41
	v_cvt_pk_bf16_f32 v161, v42, v43
	v_add_f32_e32 v36, v36, v37
	v_add_f32_e32 v38, v38, v39
	v_add_f32_e32 v40, v40, v41
	v_add_f32_e32 v42, v42, v43
	v_add_f32_e32 v36, v36, v38
	v_add_f32_e32 v40, v40, v42
	v_add_f32_e32 v36, v36, v40
	v_fma_f32 v44, v44, s3, -v166
	v_fma_f32 v45, v45, s3, -v166
	v_fma_f32 v46, v46, s3, -v166
	v_fma_f32 v47, v47, s3, -v166
	v_fma_f32 v48, v48, s3, -v166
	v_fma_f32 v49, v49, s3, -v166
	v_fma_f32 v50, v50, s3, -v166
	v_fma_f32 v51, v51, s3, -v166
	v_exp_f32_e32 v44, v44
	v_exp_f32_e32 v45, v45
	v_exp_f32_e32 v46, v46
	v_exp_f32_e32 v47, v47
	v_exp_f32_e32 v48, v48
	v_exp_f32_e32 v49, v49
	v_exp_f32_e32 v50, v50
	v_exp_f32_e32 v51, v51
	v_cvt_pk_bf16_f32 v162, v44, v45
	v_cvt_pk_bf16_f32 v163, v46, v47
	v_cvt_pk_bf16_f32 v164, v48, v49
	v_cvt_pk_bf16_f32 v165, v50, v51
	v_add_f32_e32 v44, v44, v45
	v_add_f32_e32 v46, v46, v47
	v_add_f32_e32 v48, v48, v49
	v_add_f32_e32 v50, v50, v51
	v_add_f32_e32 v44, v44, v46
	v_add_f32_e32 v48, v48, v50
	v_add_f32_e32 v44, v44, v48
	v_add_f32_e32 v52, v52, v60
	v_add_f32_e32 v36, v36, v44
	v_add_f32_e32 v52, v52, v36
	v_fma_f32 v116, v116, v168, v52
	s_waitcnt lgkmcnt(0)
	v_mfma_f32_32x32x16_bf16 v[20:35], v[118:121], v[150:153], v[20:35]
	v_mfma_f32_32x32x16_bf16 v[20:35], v[122:125], v[154:157], v[20:35]
	v_mfma_f32_32x32x16_bf16 v[20:35], v[126:129], v[158:161], v[20:35]
	v_mfma_f32_32x32x16_bf16 v[20:35], v[130:133], v[162:165], v[20:35]
	v_mfma_f32_32x32x16_bf16 v[4:19], v[134:137], v[150:153], v[4:19]
	v_mfma_f32_32x32x16_bf16 v[4:19], v[138:141], v[154:157], v[4:19]
	v_mfma_f32_32x32x16_bf16 v[4:19], v[142:145], v[158:161], v[4:19]
	v_mfma_f32_32x32x16_bf16 v[4:19], v[146:149], v[162:165], v[4:19]
	v_mov_b32_e32 v94, v166
	s_branch .LBB0_404
